# P1 and P5 GEMM epilogues: row-scale / sum-of-squares loads hoisted, one vmcnt wait per unit
# speedup vs baseline: 1.1661x; 1.0035x over previous
.LBB0_178:
	ds_read_b128 v[146:149], v157
	ds_read_b128 v[150:153], v157 offset:1024
	ds_read_b128 v[160:163], v157 offset:2048
	ds_read_b128 v[164:167], v157 offset:3072
	s_add_u32 s24, s22, 0xfff80080
	s_addc_u32 s25, s23, -1
	s_cmp_eq_u32 s83, 28
	s_cselect_b32 s27, s15, s25
	s_cselect_b32 s26, s51, s24
	s_cselect_b32 s25, s13, s82
	s_cselect_b32 s24, s80, s81
	v_lshl_add_u64 v[202:203], s[22:23], 0, v[138:139]
	s_add_i32 m0, s21, 0xc000
	ds_read_b128 v[168:171], v158
	ds_read_b128 v[172:175], v158 offset:1024
	ds_read_b128 v[178:181], v158 offset:2048
	ds_read_b128 v[182:185], v158 offset:3072
	ds_read_b128 v[186:189], v158 offset:4096
	ds_read_b128 v[190:193], v158 offset:5120
	ds_read_b128 v[194:197], v158 offset:6144
	ds_read_b128 v[198:201], v158 offset:7168
	global_load_lds_dwordx4 v[202:203], off
	v_lshl_add_u64 v[202:203], s[22:23], 0, v[140:141]
	s_add_i32 m0, s21, 0xe000
	s_nop 0
	global_load_lds_dwordx4 v[202:203], off
	s_waitcnt lgkmcnt(8)
	s_barrier
	s_waitcnt lgkmcnt(0)
	s_setprio 1
	s_waitcnt lgkmcnt(0)
	v_mfma_f32_16x16x32_bf16 v[124:127], v[146:149], v[168:171], v[124:127]
	v_mfma_f32_16x16x32_bf16 v[120:123], v[160:163], v[168:171], v[120:123]
	v_mfma_f32_16x16x32_bf16 v[108:111], v[146:149], v[178:181], v[108:111]
	v_mfma_f32_16x16x32_bf16 v[104:107], v[160:163], v[178:181], v[104:107]
	v_mfma_f32_16x16x32_bf16 v[92:95], v[146:149], v[186:189], v[92:95]
	v_mfma_f32_16x16x32_bf16 v[88:91], v[160:163], v[186:189], v[88:91]
	v_mfma_f32_16x16x32_bf16 v[84:87], v[146:149], v[194:197], v[84:87]
	v_mfma_f32_16x16x32_bf16 v[76:79], v[160:163], v[194:197], v[76:79]
	v_mfma_f32_16x16x32_bf16 v[124:127], v[150:153], v[172:175], v[124:127]
	v_mfma_f32_16x16x32_bf16 v[120:123], v[164:167], v[172:175], v[120:123]
	v_mfma_f32_16x16x32_bf16 v[108:111], v[150:153], v[182:185], v[108:111]
	v_mfma_f32_16x16x32_bf16 v[104:107], v[164:167], v[182:185], v[104:107]
	v_mfma_f32_16x16x32_bf16 v[92:95], v[150:153], v[190:193], v[92:95]
	v_mfma_f32_16x16x32_bf16 v[88:91], v[164:167], v[190:193], v[88:91]
	v_mfma_f32_16x16x32_bf16 v[84:87], v[150:153], v[198:201], v[84:87]
	v_mfma_f32_16x16x32_bf16 v[76:79], v[164:167], v[198:201], v[76:79]
	s_setprio 0
	s_barrier
	s_add_i32 s34, s45, s37
	v_lshl_add_u64 v[218:219], s[24:25], 0, v[134:135]
	s_mov_b32 m0, s34
	ds_read_b128 v[202:205], v159
	ds_read_b128 v[206:209], v159 offset:1024
	ds_read_b128 v[210:213], v159 offset:2048
	ds_read_b128 v[214:217], v159 offset:3072
	global_load_lds_dwordx4 v[218:219], off
	v_lshl_add_u64 v[220:221], s[24:25], 0, v[130:131]
	s_add_i32 m0, s34, 0x2000
	s_nop 0
	global_load_lds_dwordx4 v[220:221], off
	s_barrier
	s_waitcnt lgkmcnt(0)
	s_setprio 1
	s_waitcnt lgkmcnt(0)
	v_mfma_f32_16x16x32_bf16 v[116:119], v[202:205], v[168:171], v[116:119]
	v_mfma_f32_16x16x32_bf16 v[112:115], v[210:213], v[168:171], v[112:115]
	v_mfma_f32_16x16x32_bf16 v[100:103], v[202:205], v[178:181], v[100:103]
	v_mfma_f32_16x16x32_bf16 v[96:99], v[210:213], v[178:181], v[96:99]
	v_mfma_f32_16x16x32_bf16 v[80:83], v[202:205], v[186:189], v[80:83]
	v_mfma_f32_16x16x32_bf16 v[72:75], v[210:213], v[186:189], v[72:75]
	v_mfma_f32_16x16x32_bf16 v[68:71], v[202:205], v[194:197], v[68:71]
	v_mfma_f32_16x16x32_bf16 v[64:67], v[210:213], v[194:197], v[64:67]
	v_mfma_f32_16x16x32_bf16 v[116:119], v[206:209], v[172:175], v[116:119]
	v_mfma_f32_16x16x32_bf16 v[112:115], v[214:217], v[172:175], v[112:115]
	v_mfma_f32_16x16x32_bf16 v[100:103], v[206:209], v[182:185], v[100:103]
	v_mfma_f32_16x16x32_bf16 v[96:99], v[214:217], v[182:185], v[96:99]
	v_mfma_f32_16x16x32_bf16 v[80:83], v[206:209], v[190:193], v[80:83]
	v_mfma_f32_16x16x32_bf16 v[72:75], v[214:217], v[190:193], v[72:75]
	v_mfma_f32_16x16x32_bf16 v[68:71], v[206:209], v[198:201], v[68:71]
	v_mfma_f32_16x16x32_bf16 v[64:67], v[214:217], v[198:201], v[64:67]
	s_setprio 0
	s_mov_b32 m0, s21
	v_lshl_add_u64 v[222:223], s[26:27], 0, v[136:137]
	s_barrier
	ds_read_b128 v[168:171], v158 offset:16384
	ds_read_b128 v[172:175], v158 offset:17408
	ds_read_b128 v[178:181], v158 offset:18432
	ds_read_b128 v[182:185], v158 offset:19456
	ds_read_b128 v[186:189], v158 offset:20480
	ds_read_b128 v[190:193], v158 offset:21504
	ds_read_b128 v[194:197], v158 offset:22528
	ds_read_b128 v[198:201], v158 offset:23552
	global_load_lds_dwordx4 v[222:223], off
	v_lshl_add_u64 v[224:225], s[26:27], 0, v[132:133]
	s_mov_b32 m0, s39
	s_nop 0
	global_load_lds_dwordx4 v[224:225], off
	s_barrier
	s_waitcnt lgkmcnt(0)
	s_setprio 1
	s_waitcnt lgkmcnt(0)
	v_mfma_f32_16x16x32_bf16 v[60:63], v[146:149], v[168:171], v[60:63]
	v_mfma_f32_16x16x32_bf16 v[56:59], v[160:163], v[168:171], v[56:59]
	v_mfma_f32_16x16x32_bf16 v[48:51], v[146:149], v[178:181], v[48:51]
	v_mfma_f32_16x16x32_bf16 v[40:43], v[160:163], v[178:181], v[40:43]
	v_mfma_f32_16x16x32_bf16 v[32:35], v[146:149], v[186:189], v[32:35]
	v_mfma_f32_16x16x32_bf16 v[24:27], v[160:163], v[186:189], v[24:27]
	v_mfma_f32_16x16x32_bf16 v[12:15], v[146:149], v[194:197], v[12:15]
	v_mfma_f32_16x16x32_bf16 v[8:11], v[160:163], v[194:197], v[8:11]
	v_mfma_f32_16x16x32_bf16 v[60:63], v[150:153], v[172:175], v[60:63]
	v_mfma_f32_16x16x32_bf16 v[56:59], v[164:167], v[172:175], v[56:59]
	v_mfma_f32_16x16x32_bf16 v[48:51], v[150:153], v[182:185], v[48:51]
	v_mfma_f32_16x16x32_bf16 v[40:43], v[164:167], v[182:185], v[40:43]
	v_mfma_f32_16x16x32_bf16 v[32:35], v[150:153], v[190:193], v[32:35]
	v_mfma_f32_16x16x32_bf16 v[24:27], v[164:167], v[190:193], v[24:27]
	v_mfma_f32_16x16x32_bf16 v[12:15], v[150:153], v[198:201], v[12:15]
	v_mfma_f32_16x16x32_bf16 v[8:11], v[164:167], v[198:201], v[8:11]
	s_setprio 0
	s_barrier
	s_add_u32 s34, s24, 0x80000
	s_addc_u32 s35, s25, 0
	s_add_i32 s96, s46, s37
	v_lshl_add_u64 v[146:147], s[34:35], 0, v[134:135]
	s_mov_b32 m0, s96
	s_nop 0
	global_load_lds_dwordx4 v[146:147], off
	v_lshl_add_u64 v[146:147], s[34:35], 0, v[130:131]
	s_add_i32 m0, s96, 0x2000
	s_nop 0
	global_load_lds_dwordx4 v[146:147], off
	s_waitcnt vmcnt(6)
	s_barrier
	s_setprio 1
	v_mfma_f32_16x16x32_bf16 v[52:55], v[202:205], v[168:171], v[52:55]
	v_mfma_f32_16x16x32_bf16 v[44:47], v[210:213], v[168:171], v[44:47]
	v_mfma_f32_16x16x32_bf16 v[36:39], v[202:205], v[178:181], v[36:39]
	v_mfma_f32_16x16x32_bf16 v[28:31], v[210:213], v[178:181], v[28:31]
	v_mfma_f32_16x16x32_bf16 v[20:23], v[202:205], v[186:189], v[20:23]
	v_mfma_f32_16x16x32_bf16 v[16:19], v[210:213], v[186:189], v[16:19]
	v_mfma_f32_16x16x32_bf16 v[4:7], v[202:205], v[194:197], v[4:7]
	v_mfma_f32_16x16x32_bf16 v[0:3], v[210:213], v[194:197], v[0:3]
	v_mfma_f32_16x16x32_bf16 v[52:55], v[206:209], v[172:175], v[52:55]
	v_mfma_f32_16x16x32_bf16 v[44:47], v[214:217], v[172:175], v[44:47]
	v_mfma_f32_16x16x32_bf16 v[36:39], v[206:209], v[182:185], v[36:39]
	v_mfma_f32_16x16x32_bf16 v[28:31], v[214:217], v[182:185], v[28:31]
	v_mfma_f32_16x16x32_bf16 v[20:23], v[206:209], v[190:193], v[20:23]
	v_mfma_f32_16x16x32_bf16 v[16:19], v[214:217], v[190:193], v[16:19]
	v_mfma_f32_16x16x32_bf16 v[4:7], v[206:209], v[198:201], v[4:7]
	v_mfma_f32_16x16x32_bf16 v[0:3], v[214:217], v[198:201], v[0:3]
	s_setprio 0
	s_add_i32 s34, 0, 0x18000
	v_add_u32_e32 v164, s34, v155
	s_barrier
	ds_read_b128 v[146:149], v164
	ds_read_b128 v[150:153], v164 offset:1024
	ds_read_b128 v[160:163], v164 offset:2048
	ds_read_b128 v[164:167], v164 offset:3072
	s_add_u32 s26, s26, 0x80000
	s_addc_u32 s27, s27, 0
	s_mov_b32 m0, s40
	v_lshl_add_u64 v[202:203], s[26:27], 0, v[136:137]
	ds_read_b128 v[168:171], v158 offset:32768
	ds_read_b128 v[172:175], v158 offset:33792
	ds_read_b128 v[178:181], v158 offset:34816
	ds_read_b128 v[182:185], v158 offset:35840
	ds_read_b128 v[186:189], v158 offset:36864
	ds_read_b128 v[190:193], v158 offset:37888
	ds_read_b128 v[194:197], v158 offset:38912
	ds_read_b128 v[198:201], v158 offset:39936
	global_load_lds_dwordx4 v[202:203], off
	v_lshl_add_u64 v[202:203], s[26:27], 0, v[132:133]
	s_mov_b32 m0, s41
	s_nop 0
	global_load_lds_dwordx4 v[202:203], off
	s_waitcnt lgkmcnt(8)
	s_barrier
	s_waitcnt lgkmcnt(0)
	s_setprio 1
	s_waitcnt lgkmcnt(0)
	v_mfma_f32_16x16x32_bf16 v[124:127], v[146:149], v[168:171], v[124:127]
	v_mfma_f32_16x16x32_bf16 v[120:123], v[160:163], v[168:171], v[120:123]
	v_mfma_f32_16x16x32_bf16 v[108:111], v[146:149], v[178:181], v[108:111]
	v_mfma_f32_16x16x32_bf16 v[104:107], v[160:163], v[178:181], v[104:107]
	v_mfma_f32_16x16x32_bf16 v[92:95], v[146:149], v[186:189], v[92:95]
	v_mfma_f32_16x16x32_bf16 v[88:91], v[160:163], v[186:189], v[88:91]
	v_mfma_f32_16x16x32_bf16 v[84:87], v[146:149], v[194:197], v[84:87]
	v_mfma_f32_16x16x32_bf16 v[76:79], v[160:163], v[194:197], v[76:79]
	v_mfma_f32_16x16x32_bf16 v[124:127], v[150:153], v[172:175], v[124:127]
	v_mfma_f32_16x16x32_bf16 v[120:123], v[164:167], v[172:175], v[120:123]
	v_mfma_f32_16x16x32_bf16 v[108:111], v[150:153], v[182:185], v[108:111]
	v_mfma_f32_16x16x32_bf16 v[104:107], v[164:167], v[182:185], v[104:107]
	v_mfma_f32_16x16x32_bf16 v[92:95], v[150:153], v[190:193], v[92:95]
	v_mfma_f32_16x16x32_bf16 v[88:91], v[164:167], v[190:193], v[88:91]
	v_mfma_f32_16x16x32_bf16 v[84:87], v[150:153], v[198:201], v[84:87]
	v_mfma_f32_16x16x32_bf16 v[76:79], v[164:167], v[198:201], v[76:79]
	s_setprio 0
	s_barrier
	s_add_i32 s26, 0, 0x1c000
	s_add_i32 s27, s34, s37
	v_add_u32_e32 v177, s26, v155
	v_lshl_add_u64 v[218:219], v[218:219], 0, s[6:7]
	s_mov_b32 m0, s27
	ds_read_b128 v[202:205], v177
	ds_read_b128 v[206:209], v177 offset:1024
	ds_read_b128 v[210:213], v177 offset:2048
	ds_read_b128 v[214:217], v177 offset:3072
	global_load_lds_dwordx4 v[218:219], off
	v_lshl_add_u64 v[218:219], v[220:221], 0, s[6:7]
	s_add_i32 m0, s27, 0x2000
	s_nop 0
	global_load_lds_dwordx4 v[218:219], off
	s_barrier
	s_waitcnt lgkmcnt(0)
	s_setprio 1
	s_waitcnt lgkmcnt(0)
	v_mfma_f32_16x16x32_bf16 v[116:119], v[202:205], v[168:171], v[116:119]
	v_mfma_f32_16x16x32_bf16 v[112:115], v[210:213], v[168:171], v[112:115]
	v_mfma_f32_16x16x32_bf16 v[100:103], v[202:205], v[178:181], v[100:103]
	v_mfma_f32_16x16x32_bf16 v[96:99], v[210:213], v[178:181], v[96:99]
	v_mfma_f32_16x16x32_bf16 v[80:83], v[202:205], v[186:189], v[80:83]
	v_mfma_f32_16x16x32_bf16 v[72:75], v[210:213], v[186:189], v[72:75]
	v_mfma_f32_16x16x32_bf16 v[68:71], v[202:205], v[194:197], v[68:71]
	v_mfma_f32_16x16x32_bf16 v[64:67], v[210:213], v[194:197], v[64:67]
	v_mfma_f32_16x16x32_bf16 v[116:119], v[206:209], v[172:175], v[116:119]
	v_mfma_f32_16x16x32_bf16 v[112:115], v[214:217], v[172:175], v[112:115]
	v_mfma_f32_16x16x32_bf16 v[100:103], v[206:209], v[182:185], v[100:103]
	v_mfma_f32_16x16x32_bf16 v[96:99], v[214:217], v[182:185], v[96:99]
	v_mfma_f32_16x16x32_bf16 v[80:83], v[206:209], v[190:193], v[80:83]
	v_mfma_f32_16x16x32_bf16 v[72:75], v[214:217], v[190:193], v[72:75]
	v_mfma_f32_16x16x32_bf16 v[68:71], v[206:209], v[198:201], v[68:71]
	v_mfma_f32_16x16x32_bf16 v[64:67], v[214:217], v[198:201], v[64:67]
	s_setprio 0
	s_mov_b32 m0, s43
	v_lshl_add_u64 v[218:219], v[222:223], 0, s[6:7]
	s_barrier
	ds_read_b128 v[168:171], v158 offset:49152
	ds_read_b128 v[172:175], v158 offset:50176
	ds_read_b128 v[178:181], v158 offset:51200
	ds_read_b128 v[182:185], v158 offset:52224
	ds_read_b128 v[186:189], v158 offset:53248
	ds_read_b128 v[190:193], v158 offset:54272
	ds_read_b128 v[194:197], v158 offset:55296
	ds_read_b128 v[198:201], v158 offset:56320
	global_load_lds_dwordx4 v[218:219], off
	v_lshl_add_u64 v[218:219], v[224:225], 0, s[6:7]
	s_mov_b32 m0, s44
	s_nop 0
	global_load_lds_dwordx4 v[218:219], off
	s_barrier
	s_waitcnt lgkmcnt(0)
	s_setprio 1
	s_waitcnt lgkmcnt(0)
	v_mfma_f32_16x16x32_bf16 v[60:63], v[146:149], v[168:171], v[60:63]
	v_mfma_f32_16x16x32_bf16 v[56:59], v[160:163], v[168:171], v[56:59]
	v_mfma_f32_16x16x32_bf16 v[48:51], v[146:149], v[178:181], v[48:51]
	v_mfma_f32_16x16x32_bf16 v[40:43], v[160:163], v[178:181], v[40:43]
	v_mfma_f32_16x16x32_bf16 v[32:35], v[146:149], v[186:189], v[32:35]
	v_mfma_f32_16x16x32_bf16 v[24:27], v[160:163], v[186:189], v[24:27]
	v_mfma_f32_16x16x32_bf16 v[12:15], v[146:149], v[194:197], v[12:15]
	v_mfma_f32_16x16x32_bf16 v[8:11], v[160:163], v[194:197], v[8:11]
	v_mfma_f32_16x16x32_bf16 v[60:63], v[150:153], v[172:175], v[60:63]
	v_mfma_f32_16x16x32_bf16 v[56:59], v[164:167], v[172:175], v[56:59]
	v_mfma_f32_16x16x32_bf16 v[48:51], v[150:153], v[182:185], v[48:51]
	v_mfma_f32_16x16x32_bf16 v[40:43], v[164:167], v[182:185], v[40:43]
	v_mfma_f32_16x16x32_bf16 v[32:35], v[150:153], v[190:193], v[32:35]
	v_mfma_f32_16x16x32_bf16 v[24:27], v[164:167], v[190:193], v[24:27]
	v_mfma_f32_16x16x32_bf16 v[12:15], v[150:153], v[198:201], v[12:15]
	v_mfma_f32_16x16x32_bf16 v[8:11], v[164:167], v[198:201], v[8:11]
	s_setprio 0
	s_barrier
	s_add_u32 s24, s24, 0x80080
	s_addc_u32 s25, s25, 0
	s_add_i32 s26, s26, s37
	v_lshl_add_u64 v[146:147], s[24:25], 0, v[134:135]
	s_mov_b32 m0, s26
	s_nop 0
	global_load_lds_dwordx4 v[146:147], off
	v_lshl_add_u64 v[146:147], s[24:25], 0, v[130:131]
	s_add_i32 m0, s26, 0x2000
	s_nop 0
	global_load_lds_dwordx4 v[146:147], off
	s_waitcnt vmcnt(6)
	s_barrier
	s_setprio 1
	v_mfma_f32_16x16x32_bf16 v[52:55], v[202:205], v[168:171], v[52:55]
	v_mfma_f32_16x16x32_bf16 v[44:47], v[210:213], v[168:171], v[44:47]
	v_mfma_f32_16x16x32_bf16 v[36:39], v[202:205], v[178:181], v[36:39]
	v_mfma_f32_16x16x32_bf16 v[28:31], v[210:213], v[178:181], v[28:31]
	v_mfma_f32_16x16x32_bf16 v[20:23], v[202:205], v[186:189], v[20:23]
	v_mfma_f32_16x16x32_bf16 v[16:19], v[210:213], v[186:189], v[16:19]
	v_mfma_f32_16x16x32_bf16 v[4:7], v[202:205], v[194:197], v[4:7]
	v_mfma_f32_16x16x32_bf16 v[0:3], v[210:213], v[194:197], v[0:3]
	v_mfma_f32_16x16x32_bf16 v[52:55], v[206:209], v[172:175], v[52:55]
	v_mfma_f32_16x16x32_bf16 v[44:47], v[214:217], v[172:175], v[44:47]
	v_mfma_f32_16x16x32_bf16 v[36:39], v[206:209], v[182:185], v[36:39]
	v_mfma_f32_16x16x32_bf16 v[28:31], v[214:217], v[182:185], v[28:31]
	v_mfma_f32_16x16x32_bf16 v[20:23], v[206:209], v[190:193], v[20:23]
	v_mfma_f32_16x16x32_bf16 v[16:19], v[214:217], v[190:193], v[16:19]
	v_mfma_f32_16x16x32_bf16 v[4:7], v[206:209], v[198:201], v[4:7]
	v_mfma_f32_16x16x32_bf16 v[0:3], v[214:217], v[198:201], v[0:3]
	s_setprio 0
	s_add_i32 s83, s83, 2
	s_add_u32 s22, s22, 0x100
	s_addc_u32 s23, s23, 0
	s_add_u32 s81, s81, 0x100
	s_addc_u32 s82, s82, 0
	s_cmp_gt_u32 s83, 29
	s_barrier
	s_cbranch_scc0 .LBB0_178
	v_lshl_add_u32 v146, s20, 8, v154
	v_ashrrev_i32_e32 v147, 31, v146
	v_lshl_add_u64 v[152:153], v[146:147], 2, s[10:11]
	global_load_dword v240, v[152:153], off
	global_load_dword v242, v[152:153], off offset:64
	global_load_dword v244, v[152:153], off offset:128
	global_load_dword v246, v[152:153], off offset:192
	global_load_dword v248, v[152:153], off offset:512
	global_load_dword v250, v[152:153], off offset:576
	global_load_dword v252, v[152:153], off offset:640
	global_load_dword v254, v[152:153], off offset:704
	v_lshl_or_b32 v150, s50, 8, v156
	v_mov_b64_e32 v[148:149], s[30:31]
	v_ashrrev_i32_e32 v151, 31, v150
	v_mad_i64_i32 v[162:163], s[22:23], v146, s47, v[148:149]
	v_or_b32_e32 v164, 16, v146
	v_lshlrev_b64 v[150:151], 1, v[150:151]
	v_ashrrev_i32_e32 v165, 31, v164
	v_lshl_add_u64 v[162:163], v[162:163], 0, v[150:151]
	v_lshl_add_u64 v[166:167], v[164:165], 2, s[10:11]
	s_and_b64 vcc, exec, s[4:5]
	s_mov_b32 s50, s12
	s_mov_b32 s20, s14
	s_mov_b64 s[24:25], s[18:19]
	s_waitcnt vmcnt(0)
	v_pk_mul_f32 v[126:127], v[126:127], v[240:241] op_sel_hi:[1,0]
	v_pk_mul_f32 v[124:125], v[124:125], v[240:241] op_sel_hi:[1,0]
	v_pk_mul_f32 v[122:123], v[122:123], v[240:241] op_sel_hi:[1,0]
	v_pk_mul_f32 v[120:121], v[120:121], v[240:241] op_sel_hi:[1,0]
	v_pk_mul_f32 v[118:119], v[118:119], v[240:241] op_sel_hi:[1,0]
	v_pk_mul_f32 v[116:117], v[116:117], v[240:241] op_sel_hi:[1,0]
	v_pk_mul_f32 v[168:169], v[114:115], v[240:241] op_sel_hi:[1,0]
	v_pk_mul_f32 v[160:161], v[112:113], v[240:241] op_sel_hi:[1,0]
	v_cvt_pk_bf16_f32 v112, v124, v125
	v_cvt_pk_bf16_f32 v113, v126, v127
	v_cvt_pk_bf16_f32 v114, v120, v121
	v_cvt_pk_bf16_f32 v115, v122, v123
	v_cvt_pk_bf16_f32 v116, v116, v117
	v_cvt_pk_bf16_f32 v117, v118, v119
	v_cvt_pk_bf16_f32 v118, v160, v161
	v_cvt_pk_bf16_f32 v119, v168, v169
	global_store_dwordx4 v[162:163], v[112:115], off
	global_store_dwordx4 v[162:163], v[116:119], off offset:256
	v_or_b32_e32 v114, 32, v146
	v_mad_i64_i32 v[116:117], s[22:23], v164, s47, v[148:149]
	v_ashrrev_i32_e32 v115, 31, v114
	v_lshl_add_u64 v[116:117], v[116:117], 0, v[150:151]
	v_lshl_add_u64 v[118:119], v[114:115], 2, s[10:11]
	v_pk_mul_f32 v[110:111], v[110:111], v[242:243] op_sel_hi:[1,0]
	v_pk_mul_f32 v[108:109], v[108:109], v[242:243] op_sel_hi:[1,0]
	v_pk_mul_f32 v[106:107], v[106:107], v[242:243] op_sel_hi:[1,0]
	v_pk_mul_f32 v[104:105], v[104:105], v[242:243] op_sel_hi:[1,0]
	v_pk_mul_f32 v[102:103], v[102:103], v[242:243] op_sel_hi:[1,0]
	v_pk_mul_f32 v[100:101], v[100:101], v[242:243] op_sel_hi:[1,0]
	v_pk_mul_f32 v[120:121], v[98:99], v[242:243] op_sel_hi:[1,0]
	v_pk_mul_f32 v[112:113], v[96:97], v[242:243] op_sel_hi:[1,0]
	v_cvt_pk_bf16_f32 v96, v108, v109
	v_cvt_pk_bf16_f32 v97, v110, v111
	v_cvt_pk_bf16_f32 v98, v104, v105
	v_cvt_pk_bf16_f32 v99, v106, v107
	v_cvt_pk_bf16_f32 v100, v100, v101
	v_cvt_pk_bf16_f32 v101, v102, v103
	v_cvt_pk_bf16_f32 v102, v112, v113
	v_cvt_pk_bf16_f32 v103, v120, v121
	global_store_dwordx4 v[116:117], v[96:99], off
	global_store_dwordx4 v[116:117], v[100:103], off offset:256
	v_or_b32_e32 v98, 48, v146
	v_mad_i64_i32 v[100:101], s[22:23], v114, s47, v[148:149]
	v_ashrrev_i32_e32 v99, 31, v98
	v_lshl_add_u64 v[100:101], v[100:101], 0, v[150:151]
	v_lshl_add_u64 v[102:103], v[98:99], 2, s[10:11]
	v_pk_mul_f32 v[94:95], v[94:95], v[244:245] op_sel_hi:[1,0]
	v_pk_mul_f32 v[92:93], v[92:93], v[244:245] op_sel_hi:[1,0]
	v_pk_mul_f32 v[90:91], v[90:91], v[244:245] op_sel_hi:[1,0]
	v_pk_mul_f32 v[88:89], v[88:89], v[244:245] op_sel_hi:[1,0]
	v_pk_mul_f32 v[82:83], v[82:83], v[244:245] op_sel_hi:[1,0]
	v_pk_mul_f32 v[80:81], v[80:81], v[244:245] op_sel_hi:[1,0]
	v_pk_mul_f32 v[104:105], v[74:75], v[244:245] op_sel_hi:[1,0]
	v_pk_mul_f32 v[96:97], v[72:73], v[244:245] op_sel_hi:[1,0]
	v_cvt_pk_bf16_f32 v72, v92, v93
	v_cvt_pk_bf16_f32 v73, v94, v95
	v_cvt_pk_bf16_f32 v74, v88, v89
	v_cvt_pk_bf16_f32 v75, v90, v91
	v_cvt_pk_bf16_f32 v80, v80, v81
	v_cvt_pk_bf16_f32 v81, v82, v83
	v_cvt_pk_bf16_f32 v82, v96, v97
	v_cvt_pk_bf16_f32 v83, v104, v105
	global_store_dwordx4 v[100:101], v[72:75], off
	global_store_dwordx4 v[100:101], v[80:83], off offset:256
	v_mad_i64_i32 v[74:75], s[22:23], v98, s47, v[148:149]
	v_lshl_add_u64 v[74:75], v[74:75], 0, v[150:151]
	v_pk_mul_f32 v[80:81], v[86:87], v[246:247] op_sel_hi:[1,0]
	v_pk_mul_f32 v[82:83], v[84:85], v[246:247] op_sel_hi:[1,0]
	v_pk_mul_f32 v[78:79], v[78:79], v[246:247] op_sel_hi:[1,0]
	v_pk_mul_f32 v[76:77], v[76:77], v[246:247] op_sel_hi:[1,0]
	v_pk_mul_f32 v[70:71], v[70:71], v[246:247] op_sel_hi:[1,0]
	v_pk_mul_f32 v[68:69], v[68:69], v[246:247] op_sel_hi:[1,0]
	v_pk_mul_f32 v[84:85], v[66:67], v[246:247] op_sel_hi:[1,0]
	v_pk_mul_f32 v[72:73], v[64:65], v[246:247] op_sel_hi:[1,0]
	v_cvt_pk_bf16_f32 v64, v82, v83
	v_cvt_pk_bf16_f32 v65, v80, v81
	v_cvt_pk_bf16_f32 v66, v76, v77
	v_cvt_pk_bf16_f32 v67, v78, v79
	v_cvt_pk_bf16_f32 v68, v68, v69
	v_cvt_pk_bf16_f32 v69, v70, v71
	v_cvt_pk_bf16_f32 v70, v72, v73
	v_cvt_pk_bf16_f32 v71, v84, v85
	global_store_dwordx4 v[74:75], v[64:67], off
	global_store_dwordx4 v[74:75], v[68:71], off offset:256
	v_add_u32_e32 v65, 0x80, v146
	v_mad_i64_i32 v[66:67], s[22:23], v65, s47, v[148:149]
	v_lshl_add_u64 v[66:67], v[66:67], 0, v[150:151]
	v_pk_mul_f32 v[62:63], v[62:63], v[248:249] op_sel_hi:[1,0]
	v_pk_mul_f32 v[60:61], v[60:61], v[248:249] op_sel_hi:[1,0]
	v_pk_mul_f32 v[58:59], v[58:59], v[248:249] op_sel_hi:[1,0]
	v_pk_mul_f32 v[56:57], v[56:57], v[248:249] op_sel_hi:[1,0]
	v_pk_mul_f32 v[54:55], v[54:55], v[248:249] op_sel_hi:[1,0]
	v_pk_mul_f32 v[52:53], v[52:53], v[248:249] op_sel_hi:[1,0]
	v_pk_mul_f32 v[68:69], v[46:47], v[248:249] op_sel_hi:[1,0]
	v_pk_mul_f32 v[64:65], v[44:45], v[248:249] op_sel_hi:[1,0]
	v_cvt_pk_bf16_f32 v44, v60, v61
	v_cvt_pk_bf16_f32 v45, v62, v63
	v_cvt_pk_bf16_f32 v46, v56, v57
	v_cvt_pk_bf16_f32 v47, v58, v59
	v_cvt_pk_bf16_f32 v52, v52, v53
	v_cvt_pk_bf16_f32 v53, v54, v55
	v_cvt_pk_bf16_f32 v54, v64, v65
	v_cvt_pk_bf16_f32 v55, v68, v69
	global_store_dwordx4 v[66:67], v[44:47], off
	global_store_dwordx4 v[66:67], v[52:55], off offset:256
	v_add_u32_e32 v45, 0x90, v146
	v_mad_i64_i32 v[46:47], s[22:23], v45, s47, v[148:149]
	v_lshl_add_u64 v[46:47], v[46:47], 0, v[150:151]
	v_pk_mul_f32 v[50:51], v[50:51], v[250:251] op_sel_hi:[1,0]
	v_pk_mul_f32 v[48:49], v[48:49], v[250:251] op_sel_hi:[1,0]
	v_pk_mul_f32 v[42:43], v[42:43], v[250:251] op_sel_hi:[1,0]
	v_pk_mul_f32 v[40:41], v[40:41], v[250:251] op_sel_hi:[1,0]
	v_pk_mul_f32 v[38:39], v[38:39], v[250:251] op_sel_hi:[1,0]
	v_pk_mul_f32 v[36:37], v[36:37], v[250:251] op_sel_hi:[1,0]
	v_pk_mul_f32 v[52:53], v[30:31], v[250:251] op_sel_hi:[1,0]
	v_pk_mul_f32 v[44:45], v[28:29], v[250:251] op_sel_hi:[1,0]
	v_cvt_pk_bf16_f32 v28, v48, v49
	v_cvt_pk_bf16_f32 v29, v50, v51
	v_cvt_pk_bf16_f32 v30, v40, v41
	v_cvt_pk_bf16_f32 v31, v42, v43
	v_cvt_pk_bf16_f32 v36, v36, v37
	v_cvt_pk_bf16_f32 v37, v38, v39
	v_cvt_pk_bf16_f32 v38, v44, v45
	v_cvt_pk_bf16_f32 v39, v52, v53
	global_store_dwordx4 v[46:47], v[28:31], off
	global_store_dwordx4 v[46:47], v[36:39], off offset:256
	v_add_u32_e32 v29, 0xa0, v146
	v_mad_i64_i32 v[30:31], s[22:23], v29, s47, v[148:149]
	v_lshl_add_u64 v[30:31], v[30:31], 0, v[150:151]
	s_mov_b64 s[22:23], s[16:17]
	v_pk_mul_f32 v[34:35], v[34:35], v[252:253] op_sel_hi:[1,0]
	v_pk_mul_f32 v[32:33], v[32:33], v[252:253] op_sel_hi:[1,0]
	v_pk_mul_f32 v[26:27], v[26:27], v[252:253] op_sel_hi:[1,0]
	v_pk_mul_f32 v[24:25], v[24:25], v[252:253] op_sel_hi:[1,0]
	v_pk_mul_f32 v[22:23], v[22:23], v[252:253] op_sel_hi:[1,0]
	v_pk_mul_f32 v[20:21], v[20:21], v[252:253] op_sel_hi:[1,0]
	v_pk_mul_f32 v[36:37], v[18:19], v[252:253] op_sel_hi:[1,0]
	v_pk_mul_f32 v[28:29], v[16:17], v[252:253] op_sel_hi:[1,0]
	v_cvt_pk_bf16_f32 v16, v32, v33
	v_cvt_pk_bf16_f32 v17, v34, v35
	v_cvt_pk_bf16_f32 v18, v24, v25
	v_cvt_pk_bf16_f32 v19, v26, v27
	v_cvt_pk_bf16_f32 v20, v20, v21
	v_cvt_pk_bf16_f32 v21, v22, v23
	v_cvt_pk_bf16_f32 v22, v28, v29
	v_cvt_pk_bf16_f32 v23, v36, v37
	global_store_dwordx4 v[30:31], v[16:19], off
	global_store_dwordx4 v[30:31], v[20:23], off offset:256
	v_add_u32_e32 v17, 0xb0, v146
	v_mad_i64_i32 v[18:19], s[4:5], v17, s47, v[148:149]
	v_lshl_add_u64 v[18:19], v[18:19], 0, v[150:151]
	v_pk_mul_f32 v[14:15], v[14:15], v[254:255] op_sel_hi:[1,0]
	v_pk_mul_f32 v[12:13], v[12:13], v[254:255] op_sel_hi:[1,0]
	v_pk_mul_f32 v[10:11], v[10:11], v[254:255] op_sel_hi:[1,0]
	v_pk_mul_f32 v[8:9], v[8:9], v[254:255] op_sel_hi:[1,0]
	v_pk_mul_f32 v[6:7], v[6:7], v[254:255] op_sel_hi:[1,0]
	v_pk_mul_f32 v[4:5], v[4:5], v[254:255] op_sel_hi:[1,0]
	v_pk_mul_f32 v[20:21], v[2:3], v[254:255] op_sel_hi:[1,0]
	v_pk_mul_f32 v[16:17], v[0:1], v[254:255] op_sel_hi:[1,0]
	v_cvt_pk_bf16_f32 v0, v12, v13
	v_cvt_pk_bf16_f32 v1, v14, v15
	v_cvt_pk_bf16_f32 v2, v8, v9
	v_cvt_pk_bf16_f32 v3, v10, v11
	v_cvt_pk_bf16_f32 v4, v4, v5
	v_cvt_pk_bf16_f32 v5, v6, v7
	v_cvt_pk_bf16_f32 v6, v16, v17
	v_cvt_pk_bf16_f32 v7, v20, v21
	global_store_dwordx4 v[18:19], v[0:3], off
	global_store_dwordx4 v[18:19], v[4:7], off offset:256
	s_cbranch_vccz .LBB0_175
	s_waitcnt vmcnt(0)
	s_cmpk_gt_u32 s36, 0xff
	s_mov_b32 s43, s97
	s_cbranch_scc1 .LBB0_182
	s_barrier

.LBB0_943:
	ds_read_b128 v[146:149], v155
	ds_read_b128 v[160:163], v155 offset:1024
	ds_read_b128 v[164:167], v155 offset:2048
	ds_read_b128 v[168:171], v155 offset:3072
	s_add_u32 s20, s18, 0xfff80080
	s_addc_u32 s21, s19, -1
	s_cmp_eq_u32 s48, 28
	s_cselect_b32 s23, s11, s21
	s_cselect_b32 s22, s44, s20
	s_cselect_b32 s21, s9, s47
	s_cselect_b32 s20, s45, s46
	v_lshl_add_u64 v[150:151], s[18:19], 0, v[138:139]
	s_add_i32 m0, s17, 0xc000
	ds_read_b128 v[172:175], v156
	ds_read_b128 v[182:185], v156 offset:1024
	ds_read_b128 v[186:189], v156 offset:2048
	ds_read_b128 v[190:193], v156 offset:3072
	ds_read_b128 v[194:197], v156 offset:4096
	ds_read_b128 v[198:201], v156 offset:5120
	ds_read_b128 v[202:205], v156 offset:6144
	ds_read_b128 v[206:209], v156 offset:7168
	global_load_lds_dwordx4 v[150:151], off
	v_lshl_add_u64 v[150:151], s[18:19], 0, v[140:141]
	s_add_i32 m0, s17, 0xe000
	s_nop 0
	global_load_lds_dwordx4 v[150:151], off
	s_waitcnt lgkmcnt(8)
	s_barrier
	s_waitcnt lgkmcnt(0)
	s_setprio 1
	s_waitcnt lgkmcnt(0)
	v_mfma_f32_16x16x32_bf16 v[124:127], v[146:149], v[172:175], v[124:127]
	v_mfma_f32_16x16x32_bf16 v[120:123], v[164:167], v[172:175], v[120:123]
	v_mfma_f32_16x16x32_bf16 v[108:111], v[146:149], v[186:189], v[108:111]
	v_mfma_f32_16x16x32_bf16 v[104:107], v[164:167], v[186:189], v[104:107]
	v_mfma_f32_16x16x32_bf16 v[92:95], v[146:149], v[194:197], v[92:95]
	v_mfma_f32_16x16x32_bf16 v[88:91], v[164:167], v[194:197], v[88:91]
	v_mfma_f32_16x16x32_bf16 v[76:79], v[146:149], v[202:205], v[76:79]
	v_mfma_f32_16x16x32_bf16 v[72:75], v[164:167], v[202:205], v[72:75]
	v_mfma_f32_16x16x32_bf16 v[124:127], v[160:163], v[182:185], v[124:127]
	v_mfma_f32_16x16x32_bf16 v[120:123], v[168:171], v[182:185], v[120:123]
	v_mfma_f32_16x16x32_bf16 v[108:111], v[160:163], v[190:193], v[108:111]
	v_mfma_f32_16x16x32_bf16 v[104:107], v[168:171], v[190:193], v[104:107]
	v_mfma_f32_16x16x32_bf16 v[92:95], v[160:163], v[198:201], v[92:95]
	v_mfma_f32_16x16x32_bf16 v[88:91], v[168:171], v[198:201], v[88:91]
	v_mfma_f32_16x16x32_bf16 v[76:79], v[160:163], v[206:209], v[76:79]
	v_mfma_f32_16x16x32_bf16 v[72:75], v[168:171], v[206:209], v[72:75]
	s_setprio 0
	s_barrier
	s_add_i32 s34, s39, s25
	v_lshl_add_u64 v[150:151], s[20:21], 0, v[132:133]
	s_mov_b32 m0, s34
	ds_read_b128 v[210:213], v157
	ds_read_b128 v[214:217], v157 offset:1024
	ds_read_b128 v[218:221], v157 offset:2048
	ds_read_b128 v[222:225], v157 offset:3072
	global_load_lds_dwordx4 v[150:151], off
	v_lshl_add_u64 v[226:227], s[20:21], 0, v[128:129]
	s_add_i32 m0, s34, 0x2000
	s_nop 0
	global_load_lds_dwordx4 v[226:227], off
	s_barrier
	s_waitcnt lgkmcnt(0)
	s_setprio 1
	s_waitcnt lgkmcnt(0)
	v_mfma_f32_16x16x32_bf16 v[116:119], v[210:213], v[172:175], v[116:119]
	v_mfma_f32_16x16x32_bf16 v[112:115], v[218:221], v[172:175], v[112:115]
	v_mfma_f32_16x16x32_bf16 v[100:103], v[210:213], v[186:189], v[100:103]
	v_mfma_f32_16x16x32_bf16 v[96:99], v[218:221], v[186:189], v[96:99]
	v_mfma_f32_16x16x32_bf16 v[84:87], v[210:213], v[194:197], v[84:87]
	v_mfma_f32_16x16x32_bf16 v[80:83], v[218:221], v[194:197], v[80:83]
	v_mfma_f32_16x16x32_bf16 v[68:71], v[210:213], v[202:205], v[68:71]
	v_mfma_f32_16x16x32_bf16 v[64:67], v[218:221], v[202:205], v[64:67]
	v_mfma_f32_16x16x32_bf16 v[116:119], v[214:217], v[182:185], v[116:119]
	v_mfma_f32_16x16x32_bf16 v[112:115], v[222:225], v[182:185], v[112:115]
	v_mfma_f32_16x16x32_bf16 v[100:103], v[214:217], v[190:193], v[100:103]
	v_mfma_f32_16x16x32_bf16 v[96:99], v[222:225], v[190:193], v[96:99]
	v_mfma_f32_16x16x32_bf16 v[84:87], v[214:217], v[198:201], v[84:87]
	v_mfma_f32_16x16x32_bf16 v[80:83], v[222:225], v[198:201], v[80:83]
	v_mfma_f32_16x16x32_bf16 v[68:71], v[214:217], v[206:209], v[68:71]
	v_mfma_f32_16x16x32_bf16 v[64:67], v[222:225], v[206:209], v[64:67]
	s_setprio 0
	s_mov_b32 m0, s17
	v_lshl_add_u64 v[228:229], s[22:23], 0, v[134:135]
	s_barrier
	ds_read_b128 v[172:175], v156 offset:16384
	ds_read_b128 v[182:185], v156 offset:17408
	ds_read_b128 v[186:189], v156 offset:18432
	ds_read_b128 v[190:193], v156 offset:19456
	ds_read_b128 v[194:197], v156 offset:20480
	ds_read_b128 v[198:201], v156 offset:21504
	ds_read_b128 v[202:205], v156 offset:22528
	ds_read_b128 v[206:209], v156 offset:23552
	global_load_lds_dwordx4 v[228:229], off
	v_lshl_add_u64 v[230:231], s[22:23], 0, v[130:131]
	s_mov_b32 m0, s27
	s_nop 0
	global_load_lds_dwordx4 v[230:231], off
	s_barrier
	s_waitcnt lgkmcnt(0)
	s_setprio 1
	s_waitcnt lgkmcnt(0)
	v_mfma_f32_16x16x32_bf16 v[60:63], v[146:149], v[172:175], v[60:63]
	v_mfma_f32_16x16x32_bf16 v[56:59], v[164:167], v[172:175], v[56:59]
	v_mfma_f32_16x16x32_bf16 v[44:47], v[146:149], v[186:189], v[44:47]
	v_mfma_f32_16x16x32_bf16 v[40:43], v[164:167], v[186:189], v[40:43]
	v_mfma_f32_16x16x32_bf16 v[28:31], v[146:149], v[194:197], v[28:31]
	v_mfma_f32_16x16x32_bf16 v[24:27], v[164:167], v[194:197], v[24:27]
	v_mfma_f32_16x16x32_bf16 v[12:15], v[146:149], v[202:205], v[12:15]
	v_mfma_f32_16x16x32_bf16 v[8:11], v[164:167], v[202:205], v[8:11]
	v_mfma_f32_16x16x32_bf16 v[60:63], v[160:163], v[182:185], v[60:63]
	v_mfma_f32_16x16x32_bf16 v[56:59], v[168:171], v[182:185], v[56:59]
	v_mfma_f32_16x16x32_bf16 v[44:47], v[160:163], v[190:193], v[44:47]
	v_mfma_f32_16x16x32_bf16 v[40:43], v[168:171], v[190:193], v[40:43]
	v_mfma_f32_16x16x32_bf16 v[28:31], v[160:163], v[198:201], v[28:31]
	v_mfma_f32_16x16x32_bf16 v[24:27], v[168:171], v[198:201], v[24:27]
	v_mfma_f32_16x16x32_bf16 v[12:15], v[160:163], v[206:209], v[12:15]
	v_mfma_f32_16x16x32_bf16 v[8:11], v[168:171], v[206:209], v[8:11]
	s_setprio 0
	s_barrier
	s_add_u32 s50, s20, 0x80000
	s_addc_u32 s51, s21, 0
	s_add_i32 s34, s40, s25
	v_lshl_add_u64 v[146:147], s[50:51], 0, v[132:133]
	s_mov_b32 m0, s34
	s_nop 0
	global_load_lds_dwordx4 v[146:147], off
	v_lshl_add_u64 v[146:147], s[50:51], 0, v[128:129]
	s_add_i32 m0, s34, 0x2000
	s_nop 0
	global_load_lds_dwordx4 v[146:147], off
	s_waitcnt vmcnt(6)
	s_barrier
	s_setprio 1
	v_mfma_f32_16x16x32_bf16 v[52:55], v[210:213], v[172:175], v[52:55]
	v_mfma_f32_16x16x32_bf16 v[48:51], v[218:221], v[172:175], v[48:51]
	v_mfma_f32_16x16x32_bf16 v[36:39], v[210:213], v[186:189], v[36:39]
	v_mfma_f32_16x16x32_bf16 v[32:35], v[218:221], v[186:189], v[32:35]
	v_mfma_f32_16x16x32_bf16 v[20:23], v[210:213], v[194:197], v[20:23]
	v_mfma_f32_16x16x32_bf16 v[16:19], v[218:221], v[194:197], v[16:19]
	v_mfma_f32_16x16x32_bf16 v[4:7], v[210:213], v[202:205], v[4:7]
	v_mfma_f32_16x16x32_bf16 v[0:3], v[218:221], v[202:205], v[0:3]
	v_mfma_f32_16x16x32_bf16 v[52:55], v[214:217], v[182:185], v[52:55]
	v_mfma_f32_16x16x32_bf16 v[48:51], v[222:225], v[182:185], v[48:51]
	v_mfma_f32_16x16x32_bf16 v[36:39], v[214:217], v[190:193], v[36:39]
	v_mfma_f32_16x16x32_bf16 v[32:35], v[222:225], v[190:193], v[32:35]
	v_mfma_f32_16x16x32_bf16 v[20:23], v[214:217], v[198:201], v[20:23]
	v_mfma_f32_16x16x32_bf16 v[16:19], v[222:225], v[198:201], v[16:19]
	v_mfma_f32_16x16x32_bf16 v[4:7], v[214:217], v[206:209], v[4:7]
	v_mfma_f32_16x16x32_bf16 v[0:3], v[222:225], v[206:209], v[0:3]
	s_setprio 0
	s_add_i32 s34, 0, 0x18000
	v_add_u32_e32 v168, s34, v153
	s_barrier
	ds_read_b128 v[146:149], v168
	ds_read_b128 v[160:163], v168 offset:1024
	ds_read_b128 v[164:167], v168 offset:2048
	ds_read_b128 v[168:171], v168 offset:3072
	s_add_u32 s22, s22, 0x80000
	s_addc_u32 s23, s23, 0
	s_mov_b32 m0, s33
	v_lshl_add_u64 v[210:211], s[22:23], 0, v[134:135]
	ds_read_b128 v[172:175], v156 offset:32768
	ds_read_b128 v[182:185], v156 offset:33792
	ds_read_b128 v[186:189], v156 offset:34816
	ds_read_b128 v[190:193], v156 offset:35840
	ds_read_b128 v[194:197], v156 offset:36864
	ds_read_b128 v[198:201], v156 offset:37888
	ds_read_b128 v[202:205], v156 offset:38912
	ds_read_b128 v[206:209], v156 offset:39936
	global_load_lds_dwordx4 v[210:211], off
	v_lshl_add_u64 v[210:211], s[22:23], 0, v[130:131]
	s_mov_b32 m0, s35
	s_nop 0
	global_load_lds_dwordx4 v[210:211], off
	s_waitcnt lgkmcnt(8)
	s_barrier
	s_waitcnt lgkmcnt(0)
	s_setprio 1
	s_waitcnt lgkmcnt(0)
	v_mfma_f32_16x16x32_bf16 v[124:127], v[146:149], v[172:175], v[124:127]
	v_mfma_f32_16x16x32_bf16 v[120:123], v[164:167], v[172:175], v[120:123]
	v_mfma_f32_16x16x32_bf16 v[108:111], v[146:149], v[186:189], v[108:111]
	v_mfma_f32_16x16x32_bf16 v[104:107], v[164:167], v[186:189], v[104:107]
	v_mfma_f32_16x16x32_bf16 v[92:95], v[146:149], v[194:197], v[92:95]
	v_mfma_f32_16x16x32_bf16 v[88:91], v[164:167], v[194:197], v[88:91]
	v_mfma_f32_16x16x32_bf16 v[76:79], v[146:149], v[202:205], v[76:79]
	v_mfma_f32_16x16x32_bf16 v[72:75], v[164:167], v[202:205], v[72:75]
	v_mfma_f32_16x16x32_bf16 v[124:127], v[160:163], v[182:185], v[124:127]
	v_mfma_f32_16x16x32_bf16 v[120:123], v[168:171], v[182:185], v[120:123]
	v_mfma_f32_16x16x32_bf16 v[108:111], v[160:163], v[190:193], v[108:111]
	v_mfma_f32_16x16x32_bf16 v[104:107], v[168:171], v[190:193], v[104:107]
	v_mfma_f32_16x16x32_bf16 v[92:95], v[160:163], v[198:201], v[92:95]
	v_mfma_f32_16x16x32_bf16 v[88:91], v[168:171], v[198:201], v[88:91]
	v_mfma_f32_16x16x32_bf16 v[76:79], v[160:163], v[206:209], v[76:79]
	v_mfma_f32_16x16x32_bf16 v[72:75], v[168:171], v[206:209], v[72:75]
	s_setprio 0
	s_barrier
	s_add_i32 s22, 0, 0x1c000
	s_add_i32 s23, s34, s25
	v_add_u32_e32 v177, s22, v153
	v_lshl_add_u64 v[150:151], v[150:151], 0, s[6:7]
	s_mov_b32 m0, s23
	ds_read_b128 v[210:213], v177
	ds_read_b128 v[214:217], v177 offset:1024
	ds_read_b128 v[218:221], v177 offset:2048
	ds_read_b128 v[222:225], v177 offset:3072
	global_load_lds_dwordx4 v[150:151], off
	v_lshl_add_u64 v[150:151], v[226:227], 0, s[6:7]
	s_add_i32 m0, s23, 0x2000
	s_nop 0
	global_load_lds_dwordx4 v[150:151], off
	s_barrier
	s_waitcnt lgkmcnt(0)
	s_setprio 1
	s_waitcnt lgkmcnt(0)
	v_mfma_f32_16x16x32_bf16 v[116:119], v[210:213], v[172:175], v[116:119]
	v_mfma_f32_16x16x32_bf16 v[112:115], v[218:221], v[172:175], v[112:115]
	v_mfma_f32_16x16x32_bf16 v[100:103], v[210:213], v[186:189], v[100:103]
	v_mfma_f32_16x16x32_bf16 v[96:99], v[218:221], v[186:189], v[96:99]
	v_mfma_f32_16x16x32_bf16 v[84:87], v[210:213], v[194:197], v[84:87]
	v_mfma_f32_16x16x32_bf16 v[80:83], v[218:221], v[194:197], v[80:83]
	v_mfma_f32_16x16x32_bf16 v[68:71], v[210:213], v[202:205], v[68:71]
	v_mfma_f32_16x16x32_bf16 v[64:67], v[218:221], v[202:205], v[64:67]
	v_mfma_f32_16x16x32_bf16 v[116:119], v[214:217], v[182:185], v[116:119]
	v_mfma_f32_16x16x32_bf16 v[112:115], v[222:225], v[182:185], v[112:115]
	v_mfma_f32_16x16x32_bf16 v[100:103], v[214:217], v[190:193], v[100:103]
	v_mfma_f32_16x16x32_bf16 v[96:99], v[222:225], v[190:193], v[96:99]
	v_mfma_f32_16x16x32_bf16 v[84:87], v[214:217], v[198:201], v[84:87]
	v_mfma_f32_16x16x32_bf16 v[80:83], v[222:225], v[198:201], v[80:83]
	v_mfma_f32_16x16x32_bf16 v[68:71], v[214:217], v[206:209], v[68:71]
	v_mfma_f32_16x16x32_bf16 v[64:67], v[222:225], v[206:209], v[64:67]
	s_setprio 0
	s_mov_b32 m0, s37
	v_lshl_add_u64 v[150:151], v[228:229], 0, s[6:7]
	s_barrier
	ds_read_b128 v[172:175], v156 offset:49152
	ds_read_b128 v[182:185], v156 offset:50176
	ds_read_b128 v[186:189], v156 offset:51200
	ds_read_b128 v[190:193], v156 offset:52224
	ds_read_b128 v[194:197], v156 offset:53248
	ds_read_b128 v[198:201], v156 offset:54272
	ds_read_b128 v[202:205], v156 offset:55296
	ds_read_b128 v[206:209], v156 offset:56320
	global_load_lds_dwordx4 v[150:151], off
	v_lshl_add_u64 v[150:151], v[230:231], 0, s[6:7]
	s_mov_b32 m0, s38
	s_nop 0
	global_load_lds_dwordx4 v[150:151], off
	s_barrier
	s_waitcnt lgkmcnt(0)
	s_setprio 1
	s_waitcnt lgkmcnt(0)
	v_mfma_f32_16x16x32_bf16 v[60:63], v[146:149], v[172:175], v[60:63]
	v_mfma_f32_16x16x32_bf16 v[56:59], v[164:167], v[172:175], v[56:59]
	v_mfma_f32_16x16x32_bf16 v[44:47], v[146:149], v[186:189], v[44:47]
	v_mfma_f32_16x16x32_bf16 v[40:43], v[164:167], v[186:189], v[40:43]
	v_mfma_f32_16x16x32_bf16 v[28:31], v[146:149], v[194:197], v[28:31]
	v_mfma_f32_16x16x32_bf16 v[24:27], v[164:167], v[194:197], v[24:27]
	v_mfma_f32_16x16x32_bf16 v[12:15], v[146:149], v[202:205], v[12:15]
	v_mfma_f32_16x16x32_bf16 v[8:11], v[164:167], v[202:205], v[8:11]
	v_mfma_f32_16x16x32_bf16 v[60:63], v[160:163], v[182:185], v[60:63]
	v_mfma_f32_16x16x32_bf16 v[56:59], v[168:171], v[182:185], v[56:59]
	v_mfma_f32_16x16x32_bf16 v[44:47], v[160:163], v[190:193], v[44:47]
	v_mfma_f32_16x16x32_bf16 v[40:43], v[168:171], v[190:193], v[40:43]
	v_mfma_f32_16x16x32_bf16 v[28:31], v[160:163], v[198:201], v[28:31]
	v_mfma_f32_16x16x32_bf16 v[24:27], v[168:171], v[198:201], v[24:27]
	v_mfma_f32_16x16x32_bf16 v[12:15], v[160:163], v[206:209], v[12:15]
	v_mfma_f32_16x16x32_bf16 v[8:11], v[168:171], v[206:209], v[8:11]
	s_setprio 0
	s_barrier
	s_add_u32 s20, s20, 0x80080
	s_addc_u32 s21, s21, 0
	s_add_i32 s22, s22, s25
	v_lshl_add_u64 v[146:147], s[20:21], 0, v[132:133]
	s_mov_b32 m0, s22
	s_nop 0
	global_load_lds_dwordx4 v[146:147], off
	v_lshl_add_u64 v[146:147], s[20:21], 0, v[128:129]
	s_add_i32 m0, s22, 0x2000
	s_nop 0
	global_load_lds_dwordx4 v[146:147], off
	s_waitcnt vmcnt(6)
	s_barrier
	s_setprio 1
	v_mfma_f32_16x16x32_bf16 v[52:55], v[210:213], v[172:175], v[52:55]
	v_mfma_f32_16x16x32_bf16 v[48:51], v[218:221], v[172:175], v[48:51]
	v_mfma_f32_16x16x32_bf16 v[36:39], v[210:213], v[186:189], v[36:39]
	v_mfma_f32_16x16x32_bf16 v[32:35], v[218:221], v[186:189], v[32:35]
	v_mfma_f32_16x16x32_bf16 v[20:23], v[210:213], v[194:197], v[20:23]
	v_mfma_f32_16x16x32_bf16 v[16:19], v[218:221], v[194:197], v[16:19]
	v_mfma_f32_16x16x32_bf16 v[4:7], v[210:213], v[202:205], v[4:7]
	v_mfma_f32_16x16x32_bf16 v[0:3], v[218:221], v[202:205], v[0:3]
	v_mfma_f32_16x16x32_bf16 v[52:55], v[214:217], v[182:185], v[52:55]
	v_mfma_f32_16x16x32_bf16 v[48:51], v[222:225], v[182:185], v[48:51]
	v_mfma_f32_16x16x32_bf16 v[36:39], v[214:217], v[190:193], v[36:39]
	v_mfma_f32_16x16x32_bf16 v[32:35], v[222:225], v[190:193], v[32:35]
	v_mfma_f32_16x16x32_bf16 v[20:23], v[214:217], v[198:201], v[20:23]
	v_mfma_f32_16x16x32_bf16 v[16:19], v[222:225], v[198:201], v[16:19]
	v_mfma_f32_16x16x32_bf16 v[4:7], v[214:217], v[206:209], v[4:7]
	v_mfma_f32_16x16x32_bf16 v[0:3], v[222:225], v[206:209], v[0:3]
	s_setprio 0
	s_add_i32 s48, s48, 2
	s_add_u32 s18, s18, 0x100
	s_addc_u32 s19, s19, 0
	s_add_u32 s46, s46, 0x100
	s_addc_u32 s47, s47, 0
	s_cmp_gt_u32 s48, 29
	s_barrier
	s_cbranch_scc0 .LBB0_943
	v_and_b32_e32 v148, 64, v158
	v_xor_b32_e32 v147, 16, v158
	v_add_u32_e32 v148, 64, v148
	v_cmp_lt_i32_e32 vcc, v147, v148
	v_lshl_add_u32 v146, s16, 8, v152
	v_lshl_or_b32 v166, s43, 8, v154
	v_cndmask_b32_e32 v147, v158, v147, vcc
	v_lshlrev_b32_e32 v160, 2, v147
	v_xor_b32_e32 v147, 32, v158
	v_cmp_lt_i32_e32 vcc, v147, v148
	v_ashrrev_i32_e32 v167, 31, v166
	s_mov_b32 s43, s8
	v_cndmask_b32_e32 v147, v158, v147, vcc
	v_lshlrev_b32_e32 v161, 2, v147
	v_ashrrev_i32_e32 v147, 31, v146
	v_lshlrev_b64 v[148:149], 7, v[146:147]
	v_lshl_add_u64 v[162:163], v[136:137], 0, v[148:149]
	global_load_dwordx4 v[148:151], v[162:163], off
	global_load_dwordx4 v[168:171], v[162:163], off offset:2048
	global_load_dwordx4 v[172:175], v[162:163], off offset:2064
	v_add_co_u32_e32 v252, vcc, 0x1000, v162
	s_nop 1
	v_addc_co_u32_e32 v253, vcc, 0, v163, vcc
	v_add_co_u32_e32 v254, vcc, 0x4000, v162
	s_nop 1
	v_addc_co_u32_e32 v255, vcc, 0, v163, vcc
	global_load_dwordx4 v[182:185], v[252:253], off
	global_load_dwordx4 v[186:189], v[252:253], off offset:16
	global_load_dwordx4 v[190:193], v[252:253], off offset:2048
	global_load_dwordx4 v[194:197], v[252:253], off offset:2064
	global_load_dwordx4 v[198:201], v[254:255], off
	global_load_dwordx4 v[202:205], v[254:255], off offset:16
	global_load_dwordx4 v[206:209], v[254:255], off offset:2048
	global_load_dwordx4 v[210:213], v[254:255], off offset:2064
	v_add_co_u32_e32 v252, vcc, 0x5000, v162
	s_nop 1
	v_addc_co_u32_e32 v253, vcc, 0, v163, vcc
	global_load_dwordx4 v[214:217], v[252:253], off
	global_load_dwordx4 v[218:221], v[252:253], off offset:16
	global_load_dwordx4 v[222:225], v[252:253], off offset:2048
	global_load_dwordx4 v[240:243], v[252:253], off offset:2064
	global_load_dwordx4 v[162:165], v[162:163], off offset:16
	s_mov_b32 s16, s10
	s_mov_b64 s[20:21], s[14:15]
	s_waitcnt vmcnt(0)
	v_pk_add_f32 v[148:149], v[148:149], v[162:163]
	v_pk_add_f32 v[150:151], v[150:151], v[164:165]
	v_add_f32_e32 v147, v148, v149
	v_add_f32_e32 v147, v150, v147
	v_add_f32_e32 v147, v151, v147
	ds_bpermute_b32 v148, v160, v147
	v_lshlrev_b64 v[150:151], 1, v[166:167]
	s_waitcnt lgkmcnt(0)
	v_add_f32_e32 v147, v147, v148
	ds_bpermute_b32 v148, v161, v147
	s_waitcnt lgkmcnt(0)
	v_add_f32_e32 v147, v147, v148
	v_fmamk_f32 v147, v147, 0x3a000000, v159
	v_cmp_gt_f32_e32 vcc, s41, v147
	v_mul_f32_e32 v148, 0x4b800000, v147
	s_nop 0
	v_cndmask_b32_e32 v147, v147, v148, vcc
	v_rsq_f32_e32 v147, v147
	s_nop 0
	v_mul_f32_e32 v148, 0x45800000, v147
	v_cndmask_b32_e32 v162, v147, v148, vcc
	v_mov_b64_e32 v[148:149], s[30:31]
	v_mad_i64_i32 v[164:165], s[18:19], v146, s42, v[148:149]
	v_pk_mul_f32 v[126:127], v[126:127], v[162:163] op_sel_hi:[1,0]
	v_pk_mul_f32 v[124:125], v[124:125], v[162:163] op_sel_hi:[1,0]
	v_pk_mul_f32 v[166:167], v[122:123], v[162:163] op_sel_hi:[1,0]
	v_pk_mul_f32 v[122:123], v[120:121], v[162:163] op_sel_hi:[1,0]
	v_lshl_add_u64 v[164:165], v[164:165], 0, v[150:151]
	v_cvt_pk_bf16_f32 v120, v124, v125
	v_cvt_pk_bf16_f32 v121, v126, v127
	v_cvt_pk_bf16_f32 v122, v122, v123
	v_cvt_pk_bf16_f32 v123, v166, v167
	global_store_dwordx4 v[164:165], v[120:123], off
	v_pk_mul_f32 v[118:119], v[118:119], v[162:163] op_sel_hi:[1,0]
	v_pk_mul_f32 v[116:117], v[116:117], v[162:163] op_sel_hi:[1,0]
	v_pk_mul_f32 v[120:121], v[114:115], v[162:163] op_sel_hi:[1,0]
	v_pk_mul_f32 v[114:115], v[112:113], v[162:163] op_sel_hi:[1,0]
	v_cvt_pk_bf16_f32 v112, v116, v117
	v_cvt_pk_bf16_f32 v114, v114, v115
	v_cvt_pk_bf16_f32 v115, v120, v121
	v_or_b32_e32 v120, 16, v146
	v_cvt_pk_bf16_f32 v113, v118, v119
	v_ashrrev_i32_e32 v121, 31, v120
	global_store_dwordx4 v[164:165], v[112:115], off offset:256
	s_nop 1
	v_pk_add_f32 v[112:113], v[168:169], v[172:173]
	v_pk_add_f32 v[114:115], v[170:171], v[174:175]
	v_add_f32_e32 v112, v112, v113
	v_add_f32_e32 v112, v114, v112
	v_add_f32_e32 v112, v115, v112
	ds_bpermute_b32 v113, v160, v112
	v_mad_i64_i32 v[114:115], s[18:19], v120, s42, v[148:149]
	v_lshl_add_u64 v[114:115], v[114:115], 0, v[150:151]
	s_waitcnt lgkmcnt(0)
	v_add_f32_e32 v112, v112, v113
	ds_bpermute_b32 v113, v161, v112
	s_waitcnt lgkmcnt(0)
	v_add_f32_e32 v112, v112, v113
	v_fmamk_f32 v112, v112, 0x3a000000, v159
	v_cmp_gt_f32_e32 vcc, s41, v112
	v_mul_f32_e32 v113, 0x4b800000, v112
	s_nop 0
	v_cndmask_b32_e32 v112, v112, v113, vcc
	v_rsq_f32_e32 v112, v112
	s_nop 0
	v_mul_f32_e32 v113, 0x45800000, v112
	v_cndmask_b32_e32 v112, v112, v113, vcc
	v_pk_mul_f32 v[110:111], v[110:111], v[112:113] op_sel_hi:[1,0]
	v_pk_mul_f32 v[108:109], v[108:109], v[112:113] op_sel_hi:[1,0]
	v_pk_mul_f32 v[116:117], v[106:107], v[112:113] op_sel_hi:[1,0]
	v_pk_mul_f32 v[106:107], v[104:105], v[112:113] op_sel_hi:[1,0]
	v_cvt_pk_bf16_f32 v104, v108, v109
	v_cvt_pk_bf16_f32 v105, v110, v111
	v_cvt_pk_bf16_f32 v106, v106, v107
	v_cvt_pk_bf16_f32 v107, v116, v117
	global_store_dwordx4 v[114:115], v[104:107], off
	v_pk_mul_f32 v[102:103], v[102:103], v[112:113] op_sel_hi:[1,0]
	v_pk_mul_f32 v[100:101], v[100:101], v[112:113] op_sel_hi:[1,0]
	v_pk_mul_f32 v[104:105], v[98:99], v[112:113] op_sel_hi:[1,0]
	v_pk_mul_f32 v[98:99], v[96:97], v[112:113] op_sel_hi:[1,0]
	v_cvt_pk_bf16_f32 v96, v100, v101
	v_cvt_pk_bf16_f32 v98, v98, v99
	v_cvt_pk_bf16_f32 v99, v104, v105
	v_or_b32_e32 v104, 32, v146
	v_cvt_pk_bf16_f32 v97, v102, v103
	v_ashrrev_i32_e32 v105, 31, v104
	global_store_dwordx4 v[114:115], v[96:99], off offset:256
	s_nop 1
	v_pk_add_f32 v[96:97], v[182:183], v[186:187]
	v_pk_add_f32 v[98:99], v[184:185], v[188:189]
	v_add_f32_e32 v96, v96, v97
	v_add_f32_e32 v96, v98, v96
	v_add_f32_e32 v96, v99, v96
	ds_bpermute_b32 v97, v160, v96
	v_mad_i64_i32 v[98:99], s[18:19], v104, s42, v[148:149]
	v_lshl_add_u64 v[98:99], v[98:99], 0, v[150:151]
	s_waitcnt lgkmcnt(0)
	v_add_f32_e32 v96, v96, v97
	ds_bpermute_b32 v97, v161, v96
	s_waitcnt lgkmcnt(0)
	v_add_f32_e32 v96, v96, v97
	v_fmamk_f32 v96, v96, 0x3a000000, v159
	v_cmp_gt_f32_e32 vcc, s41, v96
	v_mul_f32_e32 v97, 0x4b800000, v96
	s_nop 0
	v_cndmask_b32_e32 v96, v96, v97, vcc
	v_rsq_f32_e32 v96, v96
	s_nop 0
	v_mul_f32_e32 v97, 0x45800000, v96
	v_cndmask_b32_e32 v96, v96, v97, vcc
	v_pk_mul_f32 v[94:95], v[94:95], v[96:97] op_sel_hi:[1,0]
	v_pk_mul_f32 v[92:93], v[92:93], v[96:97] op_sel_hi:[1,0]
	v_pk_mul_f32 v[100:101], v[90:91], v[96:97] op_sel_hi:[1,0]
	v_pk_mul_f32 v[90:91], v[88:89], v[96:97] op_sel_hi:[1,0]
	v_cvt_pk_bf16_f32 v88, v92, v93
	v_cvt_pk_bf16_f32 v89, v94, v95
	v_cvt_pk_bf16_f32 v90, v90, v91
	v_cvt_pk_bf16_f32 v91, v100, v101
	global_store_dwordx4 v[98:99], v[88:91], off
	v_pk_mul_f32 v[86:87], v[86:87], v[96:97] op_sel_hi:[1,0]
	v_pk_mul_f32 v[84:85], v[84:85], v[96:97] op_sel_hi:[1,0]
	v_pk_mul_f32 v[88:89], v[82:83], v[96:97] op_sel_hi:[1,0]
	v_pk_mul_f32 v[82:83], v[80:81], v[96:97] op_sel_hi:[1,0]
	v_cvt_pk_bf16_f32 v80, v84, v85
	v_cvt_pk_bf16_f32 v82, v82, v83
	v_cvt_pk_bf16_f32 v83, v88, v89
	v_or_b32_e32 v88, 48, v146
	v_cvt_pk_bf16_f32 v81, v86, v87
	v_ashrrev_i32_e32 v89, 31, v88
	global_store_dwordx4 v[98:99], v[80:83], off offset:256
	s_nop 1
	v_pk_add_f32 v[80:81], v[190:191], v[194:195]
	v_pk_add_f32 v[82:83], v[192:193], v[196:197]
	v_add_f32_e32 v80, v80, v81
	v_add_f32_e32 v80, v82, v80
	v_add_f32_e32 v80, v83, v80
	ds_bpermute_b32 v81, v160, v80
	v_mad_i64_i32 v[82:83], s[18:19], v88, s42, v[148:149]
	v_lshl_add_u64 v[82:83], v[82:83], 0, v[150:151]
	s_waitcnt lgkmcnt(0)
	v_add_f32_e32 v80, v80, v81
	ds_bpermute_b32 v81, v161, v80
	s_waitcnt lgkmcnt(0)
	v_add_f32_e32 v80, v80, v81
	v_fmamk_f32 v80, v80, 0x3a000000, v159
	v_cmp_gt_f32_e32 vcc, s41, v80
	v_mul_f32_e32 v81, 0x4b800000, v80
	s_nop 0
	v_cndmask_b32_e32 v80, v80, v81, vcc
	v_rsq_f32_e32 v80, v80
	s_nop 0
	v_mul_f32_e32 v81, 0x45800000, v80
	v_cndmask_b32_e32 v80, v80, v81, vcc
	v_pk_mul_f32 v[78:79], v[78:79], v[80:81] op_sel_hi:[1,0]
	v_pk_mul_f32 v[76:77], v[76:77], v[80:81] op_sel_hi:[1,0]
	v_pk_mul_f32 v[84:85], v[74:75], v[80:81] op_sel_hi:[1,0]
	v_pk_mul_f32 v[74:75], v[72:73], v[80:81] op_sel_hi:[1,0]
	v_cvt_pk_bf16_f32 v72, v76, v77
	v_cvt_pk_bf16_f32 v73, v78, v79
	v_cvt_pk_bf16_f32 v74, v74, v75
	v_cvt_pk_bf16_f32 v75, v84, v85
	global_store_dwordx4 v[82:83], v[72:75], off
	v_pk_mul_f32 v[70:71], v[70:71], v[80:81] op_sel_hi:[1,0]
	v_pk_mul_f32 v[68:69], v[68:69], v[80:81] op_sel_hi:[1,0]
	v_pk_mul_f32 v[72:73], v[66:67], v[80:81] op_sel_hi:[1,0]
	v_pk_mul_f32 v[66:67], v[64:65], v[80:81] op_sel_hi:[1,0]
	v_cvt_pk_bf16_f32 v64, v68, v69
	v_cvt_pk_bf16_f32 v66, v66, v67
	v_cvt_pk_bf16_f32 v67, v72, v73
	v_add_u32_e32 v72, 0x80, v146
	v_cvt_pk_bf16_f32 v65, v70, v71
	v_ashrrev_i32_e32 v73, 31, v72
	global_store_dwordx4 v[82:83], v[64:67], off offset:256
	s_nop 1
	v_pk_add_f32 v[64:65], v[198:199], v[202:203]
	v_pk_add_f32 v[66:67], v[200:201], v[204:205]
	v_add_f32_e32 v64, v64, v65
	v_add_f32_e32 v64, v66, v64
	v_add_f32_e32 v64, v67, v64
	ds_bpermute_b32 v65, v160, v64
	v_mad_i64_i32 v[66:67], s[18:19], v72, s42, v[148:149]
	v_lshl_add_u64 v[66:67], v[66:67], 0, v[150:151]
	s_waitcnt lgkmcnt(0)
	v_add_f32_e32 v64, v64, v65
	ds_bpermute_b32 v65, v161, v64
	s_waitcnt lgkmcnt(0)
	v_add_f32_e32 v64, v64, v65
	v_fmamk_f32 v64, v64, 0x3a000000, v159
	v_cmp_gt_f32_e32 vcc, s41, v64
	v_mul_f32_e32 v65, 0x4b800000, v64
	s_nop 0
	v_cndmask_b32_e32 v64, v64, v65, vcc
	v_rsq_f32_e32 v64, v64
	s_nop 0
	v_mul_f32_e32 v65, 0x45800000, v64
	v_cndmask_b32_e32 v64, v64, v65, vcc
	v_pk_mul_f32 v[62:63], v[62:63], v[64:65] op_sel_hi:[1,0]
	v_pk_mul_f32 v[60:61], v[60:61], v[64:65] op_sel_hi:[1,0]
	v_pk_mul_f32 v[68:69], v[58:59], v[64:65] op_sel_hi:[1,0]
	v_pk_mul_f32 v[58:59], v[56:57], v[64:65] op_sel_hi:[1,0]
	v_cvt_pk_bf16_f32 v56, v60, v61
	v_cvt_pk_bf16_f32 v57, v62, v63
	v_cvt_pk_bf16_f32 v58, v58, v59
	v_cvt_pk_bf16_f32 v59, v68, v69
	global_store_dwordx4 v[66:67], v[56:59], off
	v_pk_mul_f32 v[54:55], v[54:55], v[64:65] op_sel_hi:[1,0]
	v_pk_mul_f32 v[52:53], v[52:53], v[64:65] op_sel_hi:[1,0]
	v_pk_mul_f32 v[56:57], v[50:51], v[64:65] op_sel_hi:[1,0]
	v_pk_mul_f32 v[50:51], v[48:49], v[64:65] op_sel_hi:[1,0]
	v_cvt_pk_bf16_f32 v48, v52, v53
	v_cvt_pk_bf16_f32 v50, v50, v51
	v_cvt_pk_bf16_f32 v51, v56, v57
	v_add_u32_e32 v56, 0x90, v146
	v_cvt_pk_bf16_f32 v49, v54, v55
	v_ashrrev_i32_e32 v57, 31, v56
	global_store_dwordx4 v[66:67], v[48:51], off offset:256
	s_nop 1
	v_pk_add_f32 v[48:49], v[206:207], v[210:211]
	v_pk_add_f32 v[50:51], v[208:209], v[212:213]
	v_add_f32_e32 v48, v48, v49
	v_add_f32_e32 v48, v50, v48
	v_add_f32_e32 v48, v51, v48
	ds_bpermute_b32 v49, v160, v48
	v_mad_i64_i32 v[50:51], s[18:19], v56, s42, v[148:149]
	v_lshl_add_u64 v[50:51], v[50:51], 0, v[150:151]
	s_waitcnt lgkmcnt(0)
	v_add_f32_e32 v48, v48, v49
	ds_bpermute_b32 v49, v161, v48
	s_waitcnt lgkmcnt(0)
	v_add_f32_e32 v48, v48, v49
	v_fmamk_f32 v48, v48, 0x3a000000, v159
	v_cmp_gt_f32_e32 vcc, s41, v48
	v_mul_f32_e32 v49, 0x4b800000, v48
	s_nop 0
	v_cndmask_b32_e32 v48, v48, v49, vcc
	v_rsq_f32_e32 v48, v48
	s_nop 0
	v_mul_f32_e32 v49, 0x45800000, v48
	v_cndmask_b32_e32 v48, v48, v49, vcc
	v_pk_mul_f32 v[46:47], v[46:47], v[48:49] op_sel_hi:[1,0]
	v_pk_mul_f32 v[44:45], v[44:45], v[48:49] op_sel_hi:[1,0]
	v_pk_mul_f32 v[52:53], v[42:43], v[48:49] op_sel_hi:[1,0]
	v_pk_mul_f32 v[42:43], v[40:41], v[48:49] op_sel_hi:[1,0]
	v_cvt_pk_bf16_f32 v40, v44, v45
	v_cvt_pk_bf16_f32 v41, v46, v47
	v_cvt_pk_bf16_f32 v42, v42, v43
	v_cvt_pk_bf16_f32 v43, v52, v53
	global_store_dwordx4 v[50:51], v[40:43], off
	v_pk_mul_f32 v[38:39], v[38:39], v[48:49] op_sel_hi:[1,0]
	v_pk_mul_f32 v[36:37], v[36:37], v[48:49] op_sel_hi:[1,0]
	v_pk_mul_f32 v[40:41], v[34:35], v[48:49] op_sel_hi:[1,0]
	v_pk_mul_f32 v[34:35], v[32:33], v[48:49] op_sel_hi:[1,0]
	v_cvt_pk_bf16_f32 v32, v36, v37
	v_cvt_pk_bf16_f32 v34, v34, v35
	v_cvt_pk_bf16_f32 v35, v40, v41
	v_add_u32_e32 v40, 0xa0, v146
	v_cvt_pk_bf16_f32 v33, v38, v39
	v_ashrrev_i32_e32 v41, 31, v40
	global_store_dwordx4 v[50:51], v[32:35], off offset:256
	s_nop 1
	v_pk_add_f32 v[32:33], v[214:215], v[218:219]
	v_pk_add_f32 v[34:35], v[216:217], v[220:221]
	v_add_f32_e32 v32, v32, v33
	v_add_f32_e32 v32, v34, v32
	v_add_f32_e32 v32, v35, v32
	ds_bpermute_b32 v33, v160, v32
	v_mad_i64_i32 v[34:35], s[18:19], v40, s42, v[148:149]
	v_lshl_add_u64 v[34:35], v[34:35], 0, v[150:151]
	s_waitcnt lgkmcnt(0)
	v_add_f32_e32 v32, v32, v33
	ds_bpermute_b32 v33, v161, v32
	s_waitcnt lgkmcnt(0)
	v_add_f32_e32 v32, v32, v33
	v_fmamk_f32 v32, v32, 0x3a000000, v159
	v_cmp_gt_f32_e32 vcc, s41, v32
	v_mul_f32_e32 v33, 0x4b800000, v32
	s_nop 0
	v_cndmask_b32_e32 v32, v32, v33, vcc
	v_rsq_f32_e32 v32, v32
	s_nop 0
	v_mul_f32_e32 v33, 0x45800000, v32
	v_cndmask_b32_e32 v32, v32, v33, vcc
	v_pk_mul_f32 v[30:31], v[30:31], v[32:33] op_sel_hi:[1,0]
	v_pk_mul_f32 v[28:29], v[28:29], v[32:33] op_sel_hi:[1,0]
	v_pk_mul_f32 v[36:37], v[26:27], v[32:33] op_sel_hi:[1,0]
	v_pk_mul_f32 v[26:27], v[24:25], v[32:33] op_sel_hi:[1,0]
	v_cvt_pk_bf16_f32 v24, v28, v29
	v_cvt_pk_bf16_f32 v25, v30, v31
	v_cvt_pk_bf16_f32 v26, v26, v27
	v_cvt_pk_bf16_f32 v27, v36, v37
	global_store_dwordx4 v[34:35], v[24:27], off
	v_pk_mul_f32 v[22:23], v[22:23], v[32:33] op_sel_hi:[1,0]
	v_pk_mul_f32 v[20:21], v[20:21], v[32:33] op_sel_hi:[1,0]
	v_pk_mul_f32 v[24:25], v[18:19], v[32:33] op_sel_hi:[1,0]
	v_pk_mul_f32 v[18:19], v[16:17], v[32:33] op_sel_hi:[1,0]
	v_cvt_pk_bf16_f32 v16, v20, v21
	v_cvt_pk_bf16_f32 v18, v18, v19
	v_cvt_pk_bf16_f32 v19, v24, v25
	v_add_u32_e32 v24, 0xb0, v146
	v_cvt_pk_bf16_f32 v17, v22, v23
	v_ashrrev_i32_e32 v25, 31, v24
	global_store_dwordx4 v[34:35], v[16:19], off offset:256
	s_nop 1
	v_pk_add_f32 v[16:17], v[222:223], v[240:241]
	v_pk_add_f32 v[18:19], v[224:225], v[242:243]
	v_add_f32_e32 v16, v16, v17
	v_add_f32_e32 v16, v18, v16
	v_add_f32_e32 v16, v19, v16
	ds_bpermute_b32 v17, v160, v16
	v_mad_i64_i32 v[18:19], s[18:19], v24, s42, v[148:149]
	v_lshl_add_u64 v[18:19], v[18:19], 0, v[150:151]
	s_mov_b64 s[18:19], s[12:13]
	s_waitcnt lgkmcnt(0)
	v_add_f32_e32 v16, v16, v17
	ds_bpermute_b32 v17, v161, v16
	s_waitcnt lgkmcnt(0)
	v_add_f32_e32 v16, v16, v17
	v_fmamk_f32 v16, v16, 0x3a000000, v159
	v_cmp_gt_f32_e32 vcc, s41, v16
	v_mul_f32_e32 v17, 0x4b800000, v16
	s_nop 0
	v_cndmask_b32_e32 v16, v16, v17, vcc
	v_rsq_f32_e32 v16, v16
	s_nop 0
	v_mul_f32_e32 v17, 0x45800000, v16
	v_cndmask_b32_e32 v16, v16, v17, vcc
	v_pk_mul_f32 v[14:15], v[14:15], v[16:17] op_sel_hi:[1,0]
	v_pk_mul_f32 v[12:13], v[12:13], v[16:17] op_sel_hi:[1,0]
	v_pk_mul_f32 v[20:21], v[10:11], v[16:17] op_sel_hi:[1,0]
	v_pk_mul_f32 v[10:11], v[8:9], v[16:17] op_sel_hi:[1,0]
	v_cvt_pk_bf16_f32 v8, v12, v13
	v_cvt_pk_bf16_f32 v9, v14, v15
	v_cvt_pk_bf16_f32 v10, v10, v11
	v_cvt_pk_bf16_f32 v11, v20, v21
	global_store_dwordx4 v[18:19], v[8:11], off
	v_pk_mul_f32 v[6:7], v[6:7], v[16:17] op_sel_hi:[1,0]
	v_pk_mul_f32 v[4:5], v[4:5], v[16:17] op_sel_hi:[1,0]
	v_pk_mul_f32 v[8:9], v[2:3], v[16:17] op_sel_hi:[1,0]
	v_pk_mul_f32 v[2:3], v[0:1], v[16:17] op_sel_hi:[1,0]
	v_cvt_pk_bf16_f32 v0, v4, v5
	v_cvt_pk_bf16_f32 v1, v6, v7
	v_cvt_pk_bf16_f32 v2, v2, v3
	v_cvt_pk_bf16_f32 v3, v8, v9
	s_and_b64 vcc, exec, s[4:5]
	global_store_dwordx4 v[18:19], v[0:3], off offset:256
	s_cbranch_vccz .LBB0_940
	s_waitcnt vmcnt(0)
	s_cmpk_gt_u32 s24, 0xff
	s_cbranch_scc1 .LBB0_947
	s_barrier
